# v92 + GEMM1 accumulator zeroing with 64 v_mov_b64 instead of 128 v_mov_b32
# speedup vs baseline: 1.0036x; 1.0036x over previous
.LBB0_162:
	s_ashr_i32 s21, s20, 31
	s_lshl_b64 s[18:19], s[20:21], 19
	s_add_u32 s22, s76, s18
	s_addc_u32 s23, s77, s19
	s_and_b64 s[18:19], s[0:1], exec
	s_cselect_b32 s18, s23, s53
	s_cselect_b32 s19, s22, s52
	s_ashr_i32 s17, s16, 31
	s_lshl_b64 s[30:31], s[16:17], 19
	s_add_u32 s30, s2, s30
	s_addc_u32 s31, s24, s31
	s_and_b64 s[56:57], s[0:1], exec
	s_cselect_b32 s17, s31, s55
	s_cselect_b32 s21, s30, s54
	s_add_u32 s52, s52, 0x40080
	s_addc_u32 s53, s53, 0
	s_add_u32 s90, s54, 0x100
	v_mov_b64_e32 v[2:3], 0
	v_mov_b64_e32 v[4:5], 0
	v_mov_b64_e32 v[6:7], 0
	v_mov_b64_e32 v[8:9], 0
	v_mov_b64_e32 v[10:11], 0
	v_mov_b64_e32 v[12:13], 0
	v_mov_b64_e32 v[14:15], 0
	v_mov_b64_e32 v[16:17], 0
	v_mov_b64_e32 v[18:19], 0
	v_mov_b64_e32 v[20:21], 0
	v_mov_b64_e32 v[22:23], 0
	v_mov_b64_e32 v[24:25], 0
	v_mov_b64_e32 v[26:27], 0
	v_mov_b64_e32 v[28:29], 0
	v_mov_b64_e32 v[30:31], 0
	v_mov_b64_e32 v[32:33], 0
	v_mov_b64_e32 v[34:35], 0
	v_mov_b64_e32 v[36:37], 0
	v_mov_b64_e32 v[38:39], 0
	v_mov_b64_e32 v[40:41], 0
	v_mov_b64_e32 v[42:43], 0
	v_mov_b64_e32 v[44:45], 0
	v_mov_b64_e32 v[46:47], 0
	v_mov_b64_e32 v[48:49], 0
	v_mov_b64_e32 v[50:51], 0
	v_mov_b64_e32 v[52:53], 0
	v_mov_b64_e32 v[54:55], 0
	v_mov_b64_e32 v[56:57], 0
	v_mov_b64_e32 v[58:59], 0
	v_mov_b64_e32 v[60:61], 0
	v_mov_b64_e32 v[62:63], 0
	v_mov_b64_e32 v[64:65], 0
	v_mov_b64_e32 v[66:67], 0
	v_mov_b64_e32 v[68:69], 0
	v_mov_b64_e32 v[70:71], 0
	v_mov_b64_e32 v[72:73], 0
	v_mov_b64_e32 v[74:75], 0
	v_mov_b64_e32 v[76:77], 0
	v_mov_b64_e32 v[78:79], 0
	v_mov_b64_e32 v[80:81], 0
	v_mov_b64_e32 v[82:83], 0
	v_mov_b64_e32 v[84:85], 0
	v_mov_b64_e32 v[86:87], 0
	v_mov_b64_e32 v[88:89], 0
	v_mov_b64_e32 v[90:91], 0
	v_mov_b64_e32 v[92:93], 0
	v_mov_b64_e32 v[94:95], 0
	v_mov_b64_e32 v[96:97], 0
	v_mov_b64_e32 v[98:99], 0
	v_mov_b64_e32 v[100:101], 0
	v_mov_b64_e32 v[102:103], 0
	v_mov_b64_e32 v[104:105], 0
	v_mov_b64_e32 v[106:107], 0
	v_mov_b64_e32 v[108:109], 0
	v_mov_b64_e32 v[110:111], 0
	v_mov_b64_e32 v[112:113], 0
	v_mov_b64_e32 v[114:115], 0
	v_mov_b64_e32 v[116:117], 0
	v_mov_b64_e32 v[118:119], 0
	v_mov_b64_e32 v[120:121], 0
	v_mov_b64_e32 v[122:123], 0
	v_mov_b64_e32 v[124:125], 0
	v_mov_b64_e32 v[126:127], 0
	v_mov_b64_e32 v[128:129], 0
	s_addc_u32 s91, s55, 0
	s_mov_b32 s92, -2
